# P1 single tiles regrouped by row tile on XCDs 6/7 (column 47 moved off the pair XCDs)
# baseline (speedup 1.0000x reference)
; DI unsigned xb_ld(unsigned* p) { return __hip_atomic_load(p, __ATOMIC_RELAXED, __HIP_MEMORY_SCOPE_AGENT); }
; DI unsigned xb_add(unsigned* p, unsigned v) { return __hip_atomic_fetch_add(p, v, __ATOMIC_RELAXED, __HIP_MEMORY_SCOPE_AGENT); }
; DI int t5_bucket(int n) {
;   if (n < 16) return n;
;   int lg = 16 + (int)(logf((float)n / 16.f) / logf(8.f) * 16.f);
;   return lg < 31 ? lg : 31;
; }
; DI void xcd_barrier_complete(unsigned* bar, unsigned x, unsigned& nloc, unsigned& nx) {
;   const unsigned G = gridDim.x * gridDim.y * gridDim.z;
;   unsigned sum, cnt, mine, sp = 0u;
;   for (;;) {
;     sum = 0u; cnt = 0u; mine = 0u;
; #pragma unroll
;     for (unsigned j = 0; j < 16; ++j) { const unsigned c = xb_ld(&bar[XB_XCNT(j)]); sum += c; cnt += (c > 0u) ? 1u : 0u; mine = (j == x) ? c : mine; }
;     if (sum == G) break;
;     __builtin_amdgcn_s_sleep(1);
;     if ((++sp & 255u) == 0u) { if (xb_ld(&bar[XB_TMO])) break; if (sp > XB_SPIN_CAP) { atomicAdd(&bar[XB_TMO], 1u); break; } }
;   }
;   nloc = mine > 0u ? mine : 1u; nx = cnt > 0u ? cnt : 1u;
; }
; DI void xcd_barrier(const XcdBarrier& b) {
;   asm volatile("s_waitcnt vmcnt(0)" ::: "memory");
;   __syncthreads();
;   if (threadIdx.x == 0) {
;     unsigned* bar = b.bar;
;     __builtin_amdgcn_s_waitcnt(0);
;     unsigned nloc = b.st[0], nx = b.st[1];
;     if (nloc == 0u) { xcd_barrier_complete(bar, b.x, nloc, nx); b.st[0] = nloc; b.st[1] = nx; }
;     const unsigned old = xb_add(&bar[XB_XSUB(b.x)], 1u);
;     const unsigned gen = old / nloc;
;     if (old + 1u == (gen + 1u) * nloc) {
;       __builtin_amdgcn_fence(__ATOMIC_RELEASE, "agent");
;       asm volatile("s_waitcnt vmcnt(0)" ::: "memory");
;       const unsigned og = xb_add(&bar[XB_TOP], 1u);
;       const unsigned tg = og / nx;
;       if (og + 1u == (tg + 1u) * nx) xb_add(&bar[XB_TOPGEN], 1u);
;       else XB_SPIN(xb_ld(&bar[XB_TOPGEN]) == tg, bar);
;       __builtin_amdgcn_fence(__ATOMIC_ACQUIRE, "agent");
;       xb_add(&bar[XB_XGEN(b.x)], 1u);
;       asm volatile("s_waitcnt vmcnt(0)" ::: "memory");
;     } else {
;       XB_SPIN(xb_ld(&bar[XB_XGEN(b.x)]) == gen, bar);
;       __builtin_amdgcn_fence(__ATOMIC_ACQUIRE, "agent");
;       asm volatile("s_waitcnt vmcnt(0)" ::: "memory");
;     }
.LBB0_316:
	s_or_b64 exec, exec, s[0:1]
	v_readlane_b32 s52, v241, 40
	s_cmpk_lt_i32 s35, 0xc60
	v_readlane_b32 s56, v241, 44
	s_cselect_b64 s[0:1], -1, 0
	v_readlane_b32 s57, v241, 45
	s_add_u32 s94, s56, 0x200
	v_writelane_b32 v240, s0, 17
	s_addc_u32 s95, s57, 0
	v_cvt_f32_u32_e32 v0, v152
	v_writelane_b32 v240, s1, 18
	s_add_u32 s0, s56, 0x1000
	s_addc_u32 s1, s57, 0
	v_writelane_b32 v240, s0, 19
	v_mul_f32_e32 v0, 0x3d800000, v0
	s_mov_b32 s89, 0x7f800000
	v_writelane_b32 v240, s1, 20
	s_add_u32 s0, s56, 0x1100
	s_addc_u32 s1, s57, 0
	v_writelane_b32 v240, s0, 21
	v_mov_b32_e32 v188, 0x41b17218
	s_mov_b32 s6, 0x40051592
	v_writelane_b32 v240, s1, 22
	s_add_u32 s0, s56, 0x1200
	s_addc_u32 s1, s57, 0
	v_writelane_b32 v240, s0, 23
	v_readlane_b32 s58, v241, 46
	v_writelane_b32 v240, s1, 24
	s_mov_b32 s0, 0x800000
	v_cmp_gt_f32_e32 vcc, s0, v0
	s_add_u32 s0, s56, 0x1300
	s_addc_u32 s1, s57, 0
	v_cndmask_b32_e64 v1, 0, 32, vcc
	v_ldexp_f32 v0, v0, v1
	v_log_f32_e32 v0, v0
	v_writelane_b32 v240, s0, 25
	s_cmp_eq_u32 s5, 15
	v_readlane_b32 s48, v241, 28
	v_writelane_b32 v240, s1, 26
	s_mov_b32 s0, 0x3f317217
	v_mul_f32_e32 v1, 0x3f317217, v0
	v_fma_f32 v1, v0, s0, -v1
	v_fmac_f32_e32 v1, 0x3377d1cf, v0
	v_fmac_f32_e32 v1, 0x3f317217, v0
	v_cmp_lt_f32_e64 s[0:1], |v0|, s89
	v_readlane_b32 s49, v241, 29
	v_readlane_b32 s38, v241, 18
	v_cndmask_b32_e64 v0, v0, v1, s[0:1]
	v_cndmask_b32_e32 v1, 0, v188, vcc
	v_sub_f32_e32 v4, v0, v1
	v_div_scale_f32 v0, s[0:1], s6, s6, v4
	s_cselect_b64 s[0:1], -1, 0
	s_nop 0
	v_writelane_b32 v240, s0, 27
	s_cmp_eq_u32 s5, 14
	v_rcp_f32_e32 v1, v0
	v_writelane_b32 v240, s1, 28
	s_cselect_b64 s[0:1], -1, 0
	v_writelane_b32 v240, s0, 29
	s_cmp_eq_u32 s5, 13
	v_fma_f32 v2, -v0, v1, 1.0
	v_writelane_b32 v240, s1, 30
	s_cselect_b64 s[0:1], -1, 0
	v_writelane_b32 v240, s0, 31
	s_cmp_eq_u32 s5, 12
	v_fmac_f32_e32 v1, v2, v1
	v_writelane_b32 v240, s1, 32
	s_cselect_b64 s[0:1], -1, 0
	v_writelane_b32 v240, s0, 33
	s_cmp_eq_u32 s5, 11
	v_div_scale_f32 v2, vcc, v4, s6, v4
	v_writelane_b32 v240, s1, 34
	s_cselect_b64 s[0:1], -1, 0
	v_writelane_b32 v240, s0, 35
	s_cmp_eq_u32 s5, 10
	v_mul_f32_e32 v3, v2, v1
	v_writelane_b32 v240, s1, 36
	s_cselect_b64 s[0:1], -1, 0
	v_writelane_b32 v240, s0, 37
	s_cmp_eq_u32 s5, 9
	v_fma_f32 v5, -v0, v3, v2
	v_writelane_b32 v240, s1, 38
	s_cselect_b64 s[0:1], -1, 0
	v_writelane_b32 v240, s0, 39
	s_cmp_eq_u32 s5, 8
	v_fmac_f32_e32 v3, v5, v1
	v_writelane_b32 v240, s1, 40
	s_cselect_b64 s[0:1], -1, 0
	v_writelane_b32 v240, s0, 41
	s_cmp_eq_u32 s5, 7
	v_fma_f32 v0, -v0, v3, v2
	v_writelane_b32 v240, s1, 42
	s_cselect_b64 s[0:1], -1, 0
	v_writelane_b32 v240, s0, 43
	s_cmp_eq_u32 s5, 6
	v_div_fmas_f32 v5, v0, v1, v3
	v_writelane_b32 v240, s1, 44
	s_cselect_b64 s[0:1], -1, 0
	v_writelane_b32 v240, s0, 45
	s_cmp_eq_u32 s5, 5
	v_lshlrev_b32_e32 v0, 1, v152
	v_writelane_b32 v240, s1, 46
	s_cselect_b64 s[0:1], -1, 0
	v_writelane_b32 v240, s0, 47
	s_cmp_eq_u32 s5, 4
	v_and_b32_e32 v1, 7, v152
	v_writelane_b32 v240, s1, 48
	s_cselect_b64 s[0:1], -1, 0
	v_writelane_b32 v240, s0, 49
	s_cmp_eq_u32 s5, 3
	v_readlane_b32 s39, v241, 19
	v_writelane_b32 v240, s1, 50
	s_cselect_b64 s[0:1], -1, 0
	v_writelane_b32 v240, s0, 51
	s_cmp_eq_u32 s5, 2
	v_mov_b32_e32 v3, 0
	v_writelane_b32 v240, s1, 52
	s_cselect_b64 s[0:1], -1, 0
	v_writelane_b32 v240, s0, 53
	s_cmp_eq_u32 s5, 1
	v_readlane_b32 s53, v241, 41
	v_writelane_b32 v240, s1, 54
	s_cselect_b64 s[0:1], -1, 0
	v_writelane_b32 v240, s0, 55
	s_cmp_eq_u32 s5, 0
	v_cmp_gt_u32_e32 vcc, 16, v152
	v_writelane_b32 v240, s1, 56
	s_cselect_b64 s[0:1], -1, 0
	v_writelane_b32 v240, s0, 57
	v_readlane_b32 s59, v241, 47
	v_readlane_b32 s46, v241, 26
	v_writelane_b32 v240, s1, 58
	s_lshl_b32 s0, s4, 2
	s_add_u32 s0, s56, s0
	s_addc_u32 s1, s57, 0
	s_add_u32 s2, s0, 0x1400
	s_addc_u32 s3, s1, 0
	v_writelane_b32 v240, s2, 59
	s_add_u32 s0, s0, 0x2400
	s_addc_u32 s1, s1, 0
	v_writelane_b32 v240, s3, 60
	v_writelane_b32 v240, s0, 61
	v_readlane_b32 s47, v241, 27
	s_movk_i32 s33, 0x80
	v_writelane_b32 v240, s1, 62
	s_movk_i32 s0, 0x7f0
	v_and_or_b32 v0, v0, s0, v1
	s_add_u32 s0, s56, 0x3400
	s_addc_u32 s1, s57, 0
	v_writelane_b32 v240, s0, 63
	v_lshlrev_b32_e32 v2, 2, v0
	v_writelane_b32 v239, s1, 0
	s_add_u32 s0, s56, 0x3500
	s_addc_u32 s1, s57, 0
	s_add_i32 s7, 0, 0x23000
	s_add_i32 s4, 0, 0x23400
	v_writelane_b32 v239, s0, 1
	s_cmpk_lt_i32 s35, 0x200
	v_writelane_b32 v239, s1, 2
	s_cselect_b64 s[0:1], -1, 0
	v_writelane_b32 v239, s0, 3
	s_add_i32 s3, s35, 0x5c0
	v_mov_b32_e32 v192, 0x3ecc95a3
	v_writelane_b32 v239, s1, 4
	v_sub_co_u32_e64 v1, s[0:1], s35, 64
	s_xor_b64 s[0:1], s[0:1], -1
	s_nop 0
	v_writelane_b32 v239, s0, 5
	v_mov_b32_e32 v193, 0x260
	v_mov_b32_e32 v194, 1
	v_writelane_b32 v239, s1, 6
	s_sub_i32 s0, s58, 64
	s_cmpk_lt_i32 s35, 0x290
	v_writelane_b32 v239, s0, 7
	s_cselect_b64 s[0:1], -1, 0
	v_writelane_b32 v239, s0, 8
	s_cmp_gt_i32 s35, 63
	v_mov_b32_e32 v195, -1
	v_writelane_b32 v239, s1, 9
	s_cselect_b64 s[0:1], -1, 0
	v_writelane_b32 v239, s0, 10
	s_cmpk_gt_u32 s3, 0x7ff
	v_mov_b32_e32 v196, 0x3727c5ac
	v_writelane_b32 v239, s1, 11
	s_cselect_b64 s[0:1], -1, 0
	v_writelane_b32 v239, s0, 12
	s_cmpk_gt_u32 s3, 0x82f
	s_cselect_b64 s[8:9], -1, 0
	v_writelane_b32 v239, s1, 13
	s_mul_hi_i32 s0, s3, 0x2aaaaaab
	s_lshr_b32 s1, s0, 31
	s_ashr_i32 s0, s0, 4
	s_add_i32 s5, s0, s1
	s_lshr_b32 s0, s35, 1
	s_and_b32 s0, s0, 6
	s_lshr_b32 s1, s35, 5
	v_writelane_b32 v239, s8, 14
	s_or_b32 s2, s0, s1
	s_add_i32 s0, s35, 0xfffffd90
	v_writelane_b32 v239, s9, 15
	s_lshr_b32 s0, s0, 4
	v_writelane_b32 v239, s0, 16
	s_and_b32 s0, s3, 0xff
	s_mulk_i32 s0, 0xab
; DI void conv_weights(const Params& p, int l, char* lds, int t_first, int t_stride, int t_end) {
;     ...
;   auto loadtile = [&](int tI, float* rv, TD& d) {
;     const float* src; const float* ksc = nullptr; int ldsrc, kind, kt, ntile;
;     ...
;     else if (tI < 2048) { int u = tI - 1536; kind = 1; kt = u / 16; ntile = u % 16; src = p.w_out + (size_t)l * 2048 * DM; ldsrc = DM; d.K = 2048; d.dst = p.Wt_out + (size_t)(l & 1) * DM * 2048; }
;     else if (tI < 2096) { int u = tI - 2048; kind = 2; kt = u / 12; ntile = u % 12; src = p.w_uq + (size_t)l * 256 * 768; ldsrc = 768; d.K = 256; d.dst = p.Wt_uq; ksc = p.gq + l * 256; }
;     else { int u = tI - 2096; kind = 3; kt = u / 16; ntile = u % 16; src = p.w_ukv + (size_t)l * 128 * 1024; ldsrc = 1024; d.K = 128; d.dst = p.Wt_ukv; ksc = p.gkv + l * 128; }
;     d.k0 = kt * 64; d.n0 = ntile * 64;
;     const int n = d.n0 + nn_l;
;     int sc;
;     if (kind == 0) sc = map_in(n);
;     else if (kind == 3) sc = (n < 512) ? ((n >> 6) * 128 + (n & 63)) : (((n - 512) >> 6) * 128 + 64 + (n & 63));
;     else sc = n;
; __global__ void __launch_bounds__(NTHREADS) mega(Params p) {
;     ...
;         const int nbusy = 66 * 48 - (66 * 48 / (int)gridDim.x) * (int)gridDim.x;
;         const int nidle = (int)gridDim.x - nbusy;
;         if ((int)blockIdx.x >= nbusy && nidle > 0) conv_weights(p, l + 1, lds, (int)blockIdx.x - nbusy, nidle, 1536);
	s_lshr_b32 s0, s0, 11
	v_writelane_b32 v239, s0, 17
	s_mul_i32 s0, s0, 12
	s_sub_i32 s0, s3, s0
	s_and_b32 s0, s0, 0xff
	v_writelane_b32 v239, s0, 18
	v_readfirstlane_b32 s0, v1
	s_lshr_b32 s0, s0, 4
	v_mov_b32_e32 v197, 0x7f800000
	v_writelane_b32 v239, s0, 19
	v_writelane_b32 v239, s5, 20
	s_mul_i32 s0, s5, 0x60
	v_writelane_b32 v239, s3, 21
	s_sub_i32 s0, s3, s0
	v_writelane_b32 v239, s0, 22
	s_lshl_b32 s0, s35, 4
	s_and_b32 s1, s0, 0x100
	s_and_b32 s0, s35, 15
	v_writelane_b32 v239, s0, 23
	v_writelane_b32 v239, s1, 24
	s_bitset1_b32 s1, 14
	s_and_b32 s0, s35, 3
	v_writelane_b32 v239, s1, 25
	s_lshl_b32 s1, s1, 12
	s_add_u32 s1, s48, s1
	s_addc_u32 s3, s49, 0
	s_lshl_b32 s5, s0, 10
	s_add_u32 s8, s1, s5
	s_addc_u32 s9, s3, 0
	s_lshl_b32 s1, s2, 19
	s_add_u32 s1, s38, s1
	v_writelane_b32 v239, s8, 26
	s_addc_u32 s3, s39, 0
	s_add_u32 s1, s1, s5
	v_writelane_b32 v239, s9, 27
	v_writelane_b32 v239, s1, 28
	v_readlane_b32 s16, v241, 8
	v_readlane_b32 s17, v241, 9
	s_addc_u32 s1, s3, 0
	v_writelane_b32 v239, s1, 29
	v_lshl_add_u64 v[154:155], s[16:17], 0, v[2:3]
	v_sub_co_u32_e64 v2, s[0:1], s0, 1
	s_xor_b64 s[0:1], s[0:1], -1
	s_nop 0
	v_writelane_b32 v239, s0, 30
	v_lshlrev_b64 v[0:1], 21, v[2:3]
	v_lshl_add_u64 v[0:1], s[52:53], 0, v[0:1]
	v_writelane_b32 v239, s1, 31
	s_lshl_b32 s0, s2, 7
	s_mov_b32 s1, s61
	v_writelane_b32 v239, s0, 32
	v_writelane_b32 v239, s1, 33
	s_lshl_b64 s[0:1], s[0:1], 2
	v_lshl_add_u64 v[156:157], v[0:1], 0, s[0:1]
	v_div_fixup_f32 v0, v5, s6, v4
	v_mul_f32_e32 v0, 0x41800000, v0
	v_cvt_i32_f32_e32 v0, v0
	s_add_u32 s0, s74, s0
	s_addc_u32 s1, s75, s1
	v_writelane_b32 v239, s0, 34
	v_min_i32_e32 v0, 15, v0
	v_add_u32_e32 v0, 16, v0
	v_writelane_b32 v239, s1, 35
	s_abs_i32 s0, s58
	v_cndmask_b32_e32 v189, v0, v152, vcc
	v_cvt_f32_u32_e32 v0, s0
	s_sub_i32 s1, 0, s0
	s_mov_b32 s18, s76
	v_mov_b32_e32 v199, 0x43000000
	v_rcp_iflag_f32_e32 v0, v0
	v_mov_b32_e32 v200, 0x43800000
	v_bfrev_b32_e32 v201, 0.5
	v_mov_b32_e32 v202, 0x70
	v_mul_f32_e32 v0, 0x4f7ffffe, v0
	v_cvt_u32_f32_e32 v0, v0
	v_mov_b32_e32 v203, 0xf149f2ca
	v_mov_b32_e32 v204, 0x1200
	v_mov_b32_e32 v205, 0x80
	v_readfirstlane_b32 s2, v0
	s_mul_i32 s1, s1, s2
	s_mul_hi_u32 s1, s2, s1
	s_add_i32 s2, s2, s1
	s_mul_hi_u32 s1, s2, 0xc60
	s_mul_i32 s1, s1, s0
	s_sub_i32 s1, 0xc60, s1
	s_sub_i32 s2, s1, s0
	s_cmp_ge_u32 s1, s0
	s_cselect_b32 s1, s2, s1
	s_sub_i32 s2, s1, s0
	s_cmp_ge_u32 s1, s0
	s_cselect_b32 s5, s2, s1
	s_sub_i32 s91, s58, s5
	s_cmp_ge_i32 s35, s5
	s_cselect_b64 s[0:1], -1, 0
	s_cmp_gt_i32 s91, 0
	s_cselect_b64 s[2:3], -1, 0
	s_and_b64 s[0:1], s[0:1], s[2:3]
	v_writelane_b32 v239, s0, 36
	s_sub_i32 s2, s35, s5
	v_lshlrev_b32_e32 v0, 2, v152
	v_writelane_b32 v239, s1, 37
	s_mul_i32 s0, s59, s58
	s_mul_i32 s96, s0, s28
	s_sext_i32_i16 s0, s2
	s_cmpk_lt_i32 s2, 0x600
	s_mulk_i32 s0, 0x2aab
	v_add_u32_e32 v190, s4, v0
	s_cselect_b64 s[4:5], -1, 0
	s_lshr_b32 s1, s0, 31
	s_ashr_i32 s0, s0, 20
	s_add_i32 s0, s0, s1
	s_sext_i32_i16 s1, s0
	s_mulk_i32 s0, 0x60
	s_sub_i32 s0, s2, s0
	v_writelane_b32 v239, s4, 38
	s_sext_i32_i16 s0, s0
	s_lshl_b32 s1, s1, 6
	v_writelane_b32 v239, s5, 39
	s_lshl_b32 s0, s0, 6
	v_writelane_b32 v239, s7, 40
	s_cmpk_gt_u32 s0, 0x5ff
	v_writelane_b32 v239, s2, 41
	s_cselect_b64 s[2:3], -1, 0
	v_writelane_b32 v239, s2, 42
	s_cmpk_gt_u32 s0, 0x6ff
	v_add_u32_e32 v191, s7, v0
	v_writelane_b32 v239, s3, 43
	s_cselect_b64 s[2:3], -1, 0
	v_writelane_b32 v239, s2, 44
	s_cmpk_gt_u32 s0, 0x77f
	v_mov_b32_e32 v206, 0x1a00
	v_writelane_b32 v239, s3, 45
	s_cselect_b64 s[2:3], -1, 0
; DI int map_in(int n) {
;   if (n < 512) return n;
;   if (n < 1024) return n;
;   if (n < 1536) return 1544 + (n - 1024);
;   if (n < 1792) return 2056 + (n - 1536);
;   if (n < 1920) return 2312 + (n - 1792);
;   if (n < 2432) return 2472 + (n - 1920);
;   if (n < 2944) return 2984 + (n - 2432);
;   if (n < 3072) return 3496 + (n - 2944);
;   if (n < 3200) return 3624 + (n - 3072);
;   if (n < 3712) return 3752 + (n - 3200);
;   if (n < 4224) return 4336 + (n - 3712);
;   if (n < 4736) return 4848 + (n - 4224);
;   if (n < 4864) return 5360 + (n - 4736);
;   if (n < 5376) return 5616 + (n - 4864);
;   if (n < 5408) return 2440 + (n - 5376);
;   if (n < 5472) return 4264 + (n - 5408);
;   if (n < 5480) return 1536 + (n - 5472);
;   if (n < 5488) return 4328 + (n - 5480);
;   if (n < 5504) return -1;
;   if (n < 6016) return 1024 + (n - 5504);
;   return 5488 + (n - 6016);
; }
; __global__ void __launch_bounds__(NTHREADS) mega(Params p) {
;     ...
;         float* biasC = (float*)(lds + 143360);
;         int* btab = (int*)(lds + 143360 + 1024);
;         if (threadIdx.x < 256) biasC[threadIdx.x] = p.rel_bias[(threadIdx.x >> 3) * 16 + (threadIdx.x & 7)];
;         if (threadIdx.x < 128) btab[threadIdx.x] = t5_bucket(threadIdx.x);
	v_writelane_b32 v239, s2, 46
	s_cmpk_gt_u32 s0, 0x97f
	v_mbcnt_lo_u32_b32 v0, -1, 0
	v_writelane_b32 v239, s3, 47
	s_cselect_b64 s[2:3], -1, 0
	v_writelane_b32 v239, s2, 48
	s_cmpk_gt_u32 s0, 0xb7f
	v_mbcnt_hi_u32_b32 v198, -1, v0
	v_writelane_b32 v239, s3, 49
	s_cselect_b64 s[2:3], -1, 0
	v_writelane_b32 v239, s2, 50
	s_cmpk_gt_u32 s0, 0xbff
	s_mov_b32 s60, 0x20000
	v_writelane_b32 v239, s3, 51
	s_cselect_b64 s[2:3], -1, 0
	v_writelane_b32 v239, s2, 52
	s_cmpk_gt_u32 s0, 0xc7f
	s_movk_i32 s57, 0x90
	v_writelane_b32 v239, s3, 53
	s_cselect_b64 s[2:3], -1, 0
	v_writelane_b32 v239, s2, 54
	s_cmpk_gt_u32 s0, 0xe7f
	s_movk_i32 s53, 0x2a00
	v_writelane_b32 v239, s3, 55
	s_cselect_b64 s[2:3], -1, 0
	v_writelane_b32 v239, s2, 56
	s_cmpk_gt_u32 s0, 0x107f
	s_movk_i32 s86, 0x6f
	v_writelane_b32 v239, s3, 57
	s_cselect_b64 s[2:3], -1, 0
	v_writelane_b32 v239, s2, 58
	s_cmpk_gt_u32 s0, 0x127f
	s_mov_b32 s38, 0
	v_writelane_b32 v239, s3, 59
	s_cselect_b64 s[2:3], -1, 0
	v_writelane_b32 v239, s2, 60
	s_cmpk_gt_u32 s0, 0x12ff
	s_mov_b32 s52, 0x3e38aa3b
	v_writelane_b32 v239, s3, 61
	s_cselect_b64 s[2:3], -1, 0
	v_writelane_b32 v239, s2, 62
	s_cmpk_gt_u32 s0, 0x14ff
	s_mov_b64 s[54:55], 0x100
	v_writelane_b32 v239, s3, 63
	s_cselect_b64 s[2:3], -1, 0
	v_writelane_b32 v238, s2, 0
	s_cmpk_gt_u32 s0, 0x157f
	v_writelane_b32 v238, s3, 1
	s_cselect_b64 s[2:3], -1, 0
	v_writelane_b32 v238, s2, 2
	s_cmpk_gt_u32 s0, 0x177f
	v_writelane_b32 v238, s3, 3
	v_writelane_b32 v238, s0, 4
	s_cselect_b64 s[2:3], -1, 0
	v_writelane_b32 v238, s2, 5
	s_or_b32 s0, s1, 8
	s_ashr_i32 s19, s76, 31
	v_writelane_b32 v238, s3, 6
	v_writelane_b32 v238, s0, 7
	s_or_b32 s0, s1, 16
	v_writelane_b32 v238, s0, 8
	s_or_b32 s0, s1, 24
	v_writelane_b32 v238, s0, 9
	s_or_b32 s0, s1, 32
	v_writelane_b32 v238, s0, 10
	s_or_b32 s0, s1, 40
	v_writelane_b32 v238, s0, 11
	s_or_b32 s0, s1, 48
	v_writelane_b32 v238, s0, 12
	v_writelane_b32 v238, s1, 13
	s_or_b32 s0, s1, 56
	v_writelane_b32 v238, s0, 14
	s_lshl_b32 s0, s35, 1
	v_writelane_b32 v238, s0, 15
	v_writelane_b32 v238, s35, 16
	s_lshl_b32 s0, s35, 7
	v_writelane_b32 v238, s0, 17
	s_lshl_b32 s0, s58, 1
	v_writelane_b32 v238, s0, 18
	v_readlane_b32 s0, v241, 48
	s_add_i32 s1, s0, 0xffffff80
	v_writelane_b32 v238, s1, 19
	s_add_i32 s0, s0, s76
	v_writelane_b32 v238, s0, 20
	s_lshl_b64 s[0:1], s[18:19], 12
	v_writelane_b32 v238, s0, 21
	v_writelane_b32 v238, s1, 22
	s_add_u32 s0, s46, 0x400
	s_addc_u32 s1, s47, 0
	v_writelane_b32 v238, s0, 23
	s_add_i32 s59, 0, 0x16800
	v_writelane_b32 v238, s1, 24
	s_add_i32 s1, 0, 0xd800
	v_writelane_b32 v238, s1, 25
	s_add_i32 s1, 0, 0x10000
	v_writelane_b32 v238, s1, 26
	s_add_i32 s1, 0, 0x400
	s_movk_i32 s0, 0x100
	v_writelane_b32 v238, s1, 27
	s_add_i32 s1, 0, 0x23010
	v_writelane_b32 v238, s1, 28
	v_cmp_gt_u32_e64 s[0:1], s0, v152
	s_nop 0
	s_nop 0
	v_writelane_b32 v238, s0, 29
	s_nop 0
	s_nop 0
	v_writelane_b32 v238, s1, 30
	v_cmp_gt_u32_e64 s[0:1], s33, v152
	s_nop 0
	s_nop 0
	v_writelane_b32 v238, s0, 31
	s_nop 0
	s_nop 0
	v_writelane_b32 v238, s1, 32
	s_lshl_b64 s[0:1], s[18:19], 11
	v_writelane_b32 v238, s0, 33
	v_writelane_b32 v238, s1, 34
	s_mov_b64 s[0:1], 0
	v_writelane_b32 v238, s0, 35
	v_writelane_b32 v238, s1, 36
	v_writelane_b32 v238, s92, 37
	v_readlane_b32 s22, v241, 14
	v_writelane_b32 v238, s93, 38
	v_writelane_b32 v238, s94, 39
	v_readlane_b32 s23, v241, 15
	s_nop 0
	v_writelane_b32 v238, s95, 40
	v_writelane_b32 v238, s91, 41
	v_writelane_b32 v238, s96, 42
	v_writelane_b32 v238, s18, 43
	s_nop 1
	v_writelane_b32 v238, s19, 44
	s_branch .LBB0_320

; __global__ void __launch_bounds__(NTHREADS) mega(Params p) {
;     ...
;     for (int rep = 0; rep < REP_P1; ++rep) {
;       for (int j = blockIdx.x; j < 66 * 48; j += gridDim.x) inproj_tile(p, l, j / 48, j % 48, lds);
;       if (l < 3 && rep == 0) {
;         const int nbusy = 66 * 48 - (66 * 48 / (int)gridDim.x) * (int)gridDim.x;
;         const int nidle = (int)gridDim.x - nbusy;
;         if ((int)blockIdx.x >= nbusy && nidle > 0) conv_weights(p, l + 1, lds, (int)blockIdx.x - nbusy, nidle, 1536);
;       }
.Lpp_done:
	v_readlane_b32 s25, v238, 16
	s_and_b32 s0, s25, 7
	s_lshr_b32 s25, s25, 3
	s_cmp_lt_u32 s0, 6
	s_cbranch_scc1 .LBB0_370
	s_branch .LBB0_324

; DI void inproj_tile(const Params& p, int l, int mt, int nt, char* lds) {
;   const int tid = opaque_tid(), lane = tid & 63, w = tid >> 6, r = lane & 31, h = lane >> 5;
;   const int wm = w & 3, wn = w >> 2;
;   const int m0 = mt * 256;
;   const u16* A = p.Xb + (size_t)m0 * DM;
;   const u16* Bw = p.Wt_in + (size_t)(l & 1) * NIN * DM + (size_t)nt * 128 * DM;
;   if (nt < 42) {
;     float ssq = 0.f;
;     gemm_tile<true>(A, DM, Bw, DM, DM, lds, [&](int mi, int ni, const f32x16& a) {
;       const int tok = m0 + wm * 64 + mi * 32 + r;
;       store_rowmajor(p.H + (size_t)tok * LDH + nt * 128 + wn * 64 + ni * 32, a, h, 1.f);
;       if (nt >= 4 && nt < 8) {
;         if (ni == 0) ssq = 0.f;
; #pragma unroll
;         for (int i = 0; i < 16; ++i) ssq += a[i] * a[i];
;         if (ni == 1) {
;           float tot = ssq + __shfl_xor(ssq, 32);
;           tot = wmax(tot);
;           if (lane == 0) atomicMax(p.ctr + 64 + l * 16 + (m0 / PP) * 8 + (nt - 4) * 2 + wn, __float_as_uint(sqrtf(tot) * 1.01f));
;         }
;       }
;     });
;   } else if (nt == 42) {
;     gemm_tile<true>(A, DM, Bw, DM, DM, lds, [&](int mi, int ni, const f32x16& a) {
;       const int tok = m0 + wm * 64 + mi * 32 + r;
;       const int b = tok / PP, t = tok - b * PP;
;       const int sub = wn * 2 + ni;
;       if (sub == 0) {
;         store_rope(p.Kpe + (size_t)tok * 32, a, h, 1.f, p.ROPE + (size_t)t * 32);
;       } else if (sub == 1) {
;         store_rowmajor(p.IK + (size_t)tok * 64, a, h, 1.f);
;       } else if (sub == 2) {
;         store_rowmajor(p.IK + (size_t)tok * 64 + 32, a, h, 1.f);
;       } else {
; #pragma unroll
;         for (int e = 0; e < 4; ++e) {
;           const int hd = e + 4 * h;
;           float xv = a[e] + p.b_f[l * 8 + hd];
;           float lf = fminf(xv, 0.f) - log1pf(expf(-fabsf(xv)));
;           p.LOGF[(size_t)(b * 8 + hd) * PP + t] = lf;
;           p.IW[(size_t)tok * 8 + hd] = a[4 + e];
;         }
;       }
;     });
;   } else {
;     u16* vt; int nv, c0;
;     if (nt < 47) { vt = p.VtA; nv = 512; c0 = (nt - 43) * 128; } else { vt = p.VtD; nv = 128; c0 = 0; }
;     gemm_tile<false>(A, DM, Bw, DM, DM, lds, [&](int mi, int ni, const f32x16& a) {
; __global__ void __launch_bounds__(NTHREADS) mega(Params p) {
;     ...
;       for (int j = blockIdx.x; j < 66 * 48; j += gridDim.x) inproj_tile(p, l, j / 48, j % 48, lds);
.LBB0_323:
	s_mov_b32 s25, s101
	v_readlane_b32 s0, v238, 18
	s_add_i32 s25, s25, 32
	s_add_i32 s24, s24, s0
	s_add_i32 s23, s23, s22
	v_readlane_b32 s0, v238, 16
	s_and_b32 s0, s0, 7
	s_movk_i32 s1, 297
	s_cmp_eq_u32 s0, 6
	s_cselect_b32 s0, 363, s1
	s_cmp_ge_u32 s25, s0
	s_cbranch_scc1 .LBB0_370
.LBB0_324:
	s_mov_b32 s101, s25
	v_readlane_b32 s0, v238, 16
	s_and_b32 s0, s0, 7
	s_cmp_eq_u32 s0, 7
	s_cbranch_scc1 .Lsg_x7
	s_cmpk_lt_u32 s25, 0xc6
	s_cbranch_scc0 .Lsg_6b
	s_mul_i32 s1, s25, 0x2aab
	s_lshr_b32 s1, s1, 16
	s_mul_i32 s2, s1, 6
	s_sub_i32 s2, s25, s2
	s_branch .Lsg_6c
.Lsg_6b:
	s_sub_i32 s3, s25, 0xc6
	s_mul_i32 s1, s3, 0x3334
	s_lshr_b32 s1, s1, 16
	s_mul_i32 s2, s1, 5
	s_sub_i32 s2, s3, s2
	s_add_i32 s1, s1, 33
.Lsg_6c:
	s_add_i32 s3, s2, 4
	s_cmp_eq_u32 s2, 4
	s_cselect_b32 s3, 42, s3
	s_cmp_eq_u32 s2, 5
	s_cselect_b32 s2, 47, s3
	s_branch .Lsg_map
.Lsg_x7:
	s_cmpk_lt_u32 s25, 0x84
	s_cbranch_scc0 .Lsg_7b
	s_lshr_b32 s1, s25, 2
	s_and_b32 s2, s25, 3
	s_branch .Lsg_7c
.Lsg_7b:
	s_sub_i32 s3, s25, 0x84
	s_mul_i32 s1, s3, 0x3334
	s_lshr_b32 s1, s1, 16
	s_mul_i32 s2, s1, 5
	s_sub_i32 s2, s3, s2
	s_add_i32 s1, s1, 33
.Lsg_7c:
	s_add_i32 s2, s2, 43
